# diff_item final normalisation: the 16 serialized subln-weight and d_z loads prefetched up front with counted vmcnt
# speedup vs baseline: 1.0321x; 1.0099x over previous
; DI float bf_lo(unsigned u) { return __uint_as_float(u << 16); }
; DI float bf_hi(unsigned u) { return __uint_as_float(u & 0xffff0000u); }
; DI float frcp(float x) { return __builtin_amdgcn_rcpf(x); }
; DI void diff_item(const Params& P, int layer, int b, int hd, int qt, float lam, float omli, float negM2, char* lds) {
;     ...
;     const float inv = frcp(lsum) * lam;
;     float ss = 0.f;
; #pragma unroll
;     for (int db = 0; db < 4; ++db) {
; #pragma unroll
;         for (int i2 = 0; i2 < 2; ++i2) {
;             const u32x4 pkd = o0s[(db * 2 + i2) * 512];
; #pragma unroll
;             for (int j = 0; j < 4; ++j) {
;                 const int i = 4 * i2 + j;
;                 const float a = bf_lo(pkd[j]) - O[db][2 * i] * inv, c = bf_hi(pkd[j]) - O[db][2 * i + 1] * inv;
;                 O[db][2 * i] = a; O[db][2 * i + 1] = c; ss += a * a + c * c;
;             }
;         }
;         __builtin_amdgcn_sched_barrier(0);
;     }
;     ss += __shfl_xor(ss, 32);
;     const float rs = __builtin_amdgcn_rsqf(ss * (1.f / 128.f) + kEps) * omli;
;     const float* sw = P.subln + layer * 128;
; #pragma unroll
;     for (int db = 0; db < 4; ++db) {
; #pragma unroll
;         for (int q4 = 0; q4 < 4; ++q4) {
;             const int dv = 32 * db + 8 * q4 + 4 * h;
;             const f32x4 w4 = *(const f32x4*)(sw + dv);
;             const u32x2 z2 = *(const u32x2*)(dz + tokq * 512 + hd * 128 + dv);
.LBB0_82:
	ds_read_b128 v[116:119], v170 offset:49152
	ds_read_b128 v[120:123], v170 offset:57344
	v_mul_f32_e32 v106, v167, v0
	ds_read_b128 v[124:127], v149 offset:16384
	ds_read_b128 v[128:131], v149 offset:24576
	ds_read_b128 v[96:99], v149 offset:32768
	ds_read_b128 v[10:13], v149 offset:40960
	ds_read_b128 v[6:9], v149 offset:49152
	ds_read_b128 v[2:5], v149 offset:57344
	v_mov_b32_e32 v15, v38
	v_mov_b32_e32 v38, v37
	v_mov_b32_e32 v14, v36
	s_waitcnt lgkmcnt(1)
	v_lshlrev_b32_e32 v101, 16, v9
	v_lshlrev_b32_e32 v100, 16, v8
	v_and_b32_e32 v9, 0xffff0000, v9
	v_and_b32_e32 v8, 0xffff0000, v8
	v_pk_fma_f32 v[102:103], v[38:39], v[106:107], v[8:9] op_sel_hi:[1,0,1] neg_lo:[1,0,0] neg_hi:[1,0,0]
	v_pk_fma_f32 v[100:101], v[14:15], v[106:107], v[100:101] op_sel_hi:[1,0,1] neg_lo:[1,0,0] neg_hi:[1,0,0]
	v_pk_mul_f32 v[8:9], v[102:103], v[102:103]
	v_mov_b32_e32 v15, v42
	v_pk_fma_f32 v[104:105], v[100:101], v[100:101], v[8:9]
	s_waitcnt lgkmcnt(0)
	v_lshlrev_b32_e32 v9, 16, v3
	v_lshlrev_b32_e32 v8, 16, v2
	v_and_b32_e32 v3, 0xffff0000, v3
	v_and_b32_e32 v2, 0xffff0000, v2
	v_mov_b32_e32 v42, v41
	v_mov_b32_e32 v14, v40
	v_pk_fma_f32 v[40:41], v[42:43], v[106:107], v[2:3] op_sel_hi:[1,0,1] neg_lo:[1,0,0] neg_hi:[1,0,0]
	v_pk_fma_f32 v[38:39], v[14:15], v[106:107], v[8:9] op_sel_hi:[1,0,1] neg_lo:[1,0,0] neg_hi:[1,0,0]
	v_pk_mul_f32 v[2:3], v[40:41], v[40:41]
	v_mov_b32_e32 v8, v44
	v_pk_fma_f32 v[108:109], v[38:39], v[38:39], v[2:3]
	v_lshlrev_b32_e32 v3, 16, v5
	v_lshlrev_b32_e32 v2, 16, v4
	v_mov_b32_e32 v9, v46
	v_pk_fma_f32 v[8:9], v[8:9], v[106:107], v[2:3] op_sel_hi:[1,0,1] neg_lo:[1,0,0] neg_hi:[1,0,0]
	v_and_b32_e32 v3, 0xffff0000, v5
	v_and_b32_e32 v2, 0xffff0000, v4
	v_mov_b32_e32 v46, v45
	v_pk_fma_f32 v[14:15], v[46:47], v[106:107], v[2:3] op_sel_hi:[1,0,1] neg_lo:[1,0,0] neg_hi:[1,0,0]
	s_nop 0
	v_pk_mul_f32 v[2:3], v[14:15], v[14:15]
	s_nop 0
	v_pk_fma_f32 v[114:115], v[8:9], v[8:9], v[2:3]
	v_lshrrev_b32_e32 v0, 3, v169
	v_and_b32_e32 v0, 4, v0
	v_lshl_add_u64 v[36:37], s[16:17], 0, v[146:147]
	v_lshlrev_b32_e32 v107, 2, v0
	v_lshlrev_b32_e32 v0, 1, v0
	v_lshl_add_u64 v[36:37], v[36:37], 0, v[0:1]
	global_load_dwordx4 v[204:207], v107, s[6:7]
	global_load_dwordx2 v[154:155], v[36:37], off
	global_load_dwordx4 v[208:211], v107, s[6:7] offset:32
	global_load_dwordx2 v[156:157], v[36:37], off offset:16
	global_load_dwordx4 v[212:215], v107, s[6:7] offset:64
	global_load_dwordx2 v[158:159], v[36:37], off offset:32
	global_load_dwordx4 v[216:219], v107, s[6:7] offset:96
	global_load_dwordx2 v[160:161], v[36:37], off offset:48
	global_load_dwordx4 v[220:223], v107, s[6:7] offset:128
	global_load_dwordx2 v[164:165], v[36:37], off offset:64
	global_load_dwordx4 v[224:227], v107, s[6:7] offset:160
	global_load_dwordx2 v[170:171], v[36:37], off offset:80
	global_load_dwordx4 v[228:231], v107, s[6:7] offset:192
	global_load_dwordx2 v[172:173], v[36:37], off offset:96
	global_load_dwordx4 v[232:235], v107, s[6:7] offset:224
	global_load_dwordx2 v[184:185], v[36:37], off offset:112
	global_load_dwordx4 v[236:239], v107, s[6:7] offset:256
	global_load_dwordx2 v[186:187], v[36:37], off offset:128
	global_load_dwordx4 v[240:243], v107, s[6:7] offset:288
	global_load_dwordx2 v[188:189], v[36:37], off offset:144
	global_load_dwordx4 v[244:247], v107, s[6:7] offset:320
	global_load_dwordx2 v[190:191], v[36:37], off offset:160
	global_load_dwordx4 v[248:251], v107, s[6:7] offset:352
	global_load_dwordx2 v[192:193], v[36:37], off offset:176
	global_load_dwordx2 v[194:195], v[36:37], off offset:192
	global_load_dwordx2 v[196:197], v[36:37], off offset:208
	global_load_dwordx2 v[198:199], v[36:37], off offset:224
	global_load_dwordx2 v[200:201], v[36:37], off offset:240
	v_lshlrev_b32_e32 v42, 16, v117
	v_and_b32_e32 v43, 0xffff0000, v117
	v_pk_fma_f32 v[112:113], v[82:83], v[106:107], v[42:43] op_sel_hi:[1,0,1] neg_lo:[1,0,0] neg_hi:[1,0,0]
	v_lshlrev_b32_e32 v42, 16, v116
	v_and_b32_e32 v43, 0xffff0000, v116
	v_pk_fma_f32 v[116:117], v[80:81], v[106:107], v[42:43] op_sel_hi:[1,0,1] neg_lo:[1,0,0] neg_hi:[1,0,0]
	v_lshlrev_b32_e32 v42, 16, v119
	v_and_b32_e32 v43, 0xffff0000, v119
	v_pk_fma_f32 v[86:87], v[86:87], v[106:107], v[42:43] op_sel_hi:[1,0,1] neg_lo:[1,0,0] neg_hi:[1,0,0]
	v_lshlrev_b32_e32 v42, 16, v118
	v_and_b32_e32 v43, 0xffff0000, v118
	v_pk_fma_f32 v[118:119], v[84:85], v[106:107], v[42:43] op_sel_hi:[1,0,1] neg_lo:[1,0,0] neg_hi:[1,0,0]
	v_lshlrev_b32_e32 v42, 16, v121
	v_and_b32_e32 v43, 0xffff0000, v121
	v_pk_fma_f32 v[90:91], v[90:91], v[106:107], v[42:43] op_sel_hi:[1,0,1] neg_lo:[1,0,0] neg_hi:[1,0,0]
	v_lshlrev_b32_e32 v42, 16, v120
	v_and_b32_e32 v43, 0xffff0000, v120
	v_pk_fma_f32 v[120:121], v[88:89], v[106:107], v[42:43] op_sel_hi:[1,0,1] neg_lo:[1,0,0] neg_hi:[1,0,0]
	v_lshlrev_b32_e32 v42, 16, v123
	v_and_b32_e32 v43, 0xffff0000, v123
	v_pk_fma_f32 v[88:89], v[94:95], v[106:107], v[42:43] op_sel_hi:[1,0,1] neg_lo:[1,0,0] neg_hi:[1,0,0]
	v_lshlrev_b32_e32 v42, 16, v122
	v_and_b32_e32 v43, 0xffff0000, v122
	v_pk_fma_f32 v[92:93], v[92:93], v[106:107], v[42:43] op_sel_hi:[1,0,1] neg_lo:[1,0,0] neg_hi:[1,0,0]
	v_lshlrev_b32_e32 v42, 16, v125
	v_and_b32_e32 v43, 0xffff0000, v125
	v_pk_fma_f32 v[84:85], v[66:67], v[106:107], v[42:43] op_sel_hi:[1,0,1] neg_lo:[1,0,0] neg_hi:[1,0,0]
	v_lshlrev_b32_e32 v42, 16, v124
	v_and_b32_e32 v43, 0xffff0000, v124
	v_pk_fma_f32 v[94:95], v[64:65], v[106:107], v[42:43] op_sel_hi:[1,0,1] neg_lo:[1,0,0] neg_hi:[1,0,0]
	v_lshlrev_b32_e32 v42, 16, v127
	v_and_b32_e32 v43, 0xffff0000, v127
	v_pk_fma_f32 v[80:81], v[70:71], v[106:107], v[42:43] op_sel_hi:[1,0,1] neg_lo:[1,0,0] neg_hi:[1,0,0]
; DI float bf_lo(unsigned u) { return __uint_as_float(u << 16); }
; DI float bf_hi(unsigned u) { return __uint_as_float(u & 0xffff0000u); }
; DI void diff_item(const Params& P, int layer, int b, int hd, int qt, float lam, float omli, float negM2, char* lds) {
;     ...
;     float ss = 0.f;
; #pragma unroll
;     for (int db = 0; db < 4; ++db) {
; #pragma unroll
;         for (int i2 = 0; i2 < 2; ++i2) {
;             const u32x4 pkd = o0s[(db * 2 + i2) * 512];
; #pragma unroll
;             for (int j = 0; j < 4; ++j) {
;                 const int i = 4 * i2 + j;
;                 const float a = bf_lo(pkd[j]) - O[db][2 * i] * inv, c = bf_hi(pkd[j]) - O[db][2 * i + 1] * inv;
;                 O[db][2 * i] = a; O[db][2 * i + 1] = c; ss += a * a + c * c;
;             }
;         }
;         __builtin_amdgcn_sched_barrier(0);
;     }
;     ss += __shfl_xor(ss, 32);
	v_lshlrev_b32_e32 v42, 16, v126
	v_and_b32_e32 v43, 0xffff0000, v126
	v_pk_fma_f32 v[82:83], v[68:69], v[106:107], v[42:43] op_sel_hi:[1,0,1] neg_lo:[1,0,0] neg_hi:[1,0,0]
	v_lshlrev_b32_e32 v42, 16, v129
	v_and_b32_e32 v43, 0xffff0000, v129
	v_pk_fma_f32 v[74:75], v[74:75], v[106:107], v[42:43] op_sel_hi:[1,0,1] neg_lo:[1,0,0] neg_hi:[1,0,0]
	v_lshlrev_b32_e32 v42, 16, v128
	v_and_b32_e32 v43, 0xffff0000, v128
	v_pk_fma_f32 v[72:73], v[72:73], v[106:107], v[42:43] op_sel_hi:[1,0,1] neg_lo:[1,0,0] neg_hi:[1,0,0]
	v_lshlrev_b32_e32 v42, 16, v131
	v_and_b32_e32 v43, 0xffff0000, v131
	v_pk_fma_f32 v[68:69], v[78:79], v[106:107], v[42:43] op_sel_hi:[1,0,1] neg_lo:[1,0,0] neg_hi:[1,0,0]
	v_lshlrev_b32_e32 v42, 16, v130
	v_and_b32_e32 v43, 0xffff0000, v130
	v_pk_fma_f32 v[70:71], v[76:77], v[106:107], v[42:43] op_sel_hi:[1,0,1] neg_lo:[1,0,0] neg_hi:[1,0,0]
	v_lshlrev_b32_e32 v42, 16, v97
	v_and_b32_e32 v43, 0xffff0000, v97
	v_pk_fma_f32 v[64:65], v[50:51], v[106:107], v[42:43] op_sel_hi:[1,0,1] neg_lo:[1,0,0] neg_hi:[1,0,0]
	v_lshlrev_b32_e32 v42, 16, v96
	v_and_b32_e32 v43, 0xffff0000, v96
	v_pk_fma_f32 v[66:67], v[48:49], v[106:107], v[42:43] op_sel_hi:[1,0,1] neg_lo:[1,0,0] neg_hi:[1,0,0]
	v_lshlrev_b32_e32 v42, 16, v99
	v_and_b32_e32 v43, 0xffff0000, v99
	v_pk_fma_f32 v[50:51], v[54:55], v[106:107], v[42:43] op_sel_hi:[1,0,1] neg_lo:[1,0,0] neg_hi:[1,0,0]
	v_lshlrev_b32_e32 v42, 16, v98
	v_and_b32_e32 v43, 0xffff0000, v98
	v_pk_fma_f32 v[52:53], v[52:53], v[106:107], v[42:43] op_sel_hi:[1,0,1] neg_lo:[1,0,0] neg_hi:[1,0,0]
	v_lshlrev_b32_e32 v42, 16, v11
	v_and_b32_e32 v43, 0xffff0000, v11
	v_pk_fma_f32 v[46:47], v[58:59], v[106:107], v[42:43] op_sel_hi:[1,0,1] neg_lo:[1,0,0] neg_hi:[1,0,0]
	v_lshlrev_b32_e32 v42, 16, v10
	v_and_b32_e32 v43, 0xffff0000, v10
	v_lshlrev_b32_e32 v10, 16, v13
	v_and_b32_e32 v11, 0xffff0000, v13
	v_pk_fma_f32 v[48:49], v[56:57], v[106:107], v[42:43] op_sel_hi:[1,0,1] neg_lo:[1,0,0] neg_hi:[1,0,0]
	v_pk_fma_f32 v[42:43], v[62:63], v[106:107], v[10:11] op_sel_hi:[1,0,1] neg_lo:[1,0,0] neg_hi:[1,0,0]
	v_lshlrev_b32_e32 v10, 16, v12
	v_and_b32_e32 v11, 0xffff0000, v12
	v_pk_mul_f32 v[132:133], v[112:113], v[112:113]
	v_pk_mul_f32 v[134:135], v[116:117], v[116:117]
	v_pk_fma_f32 v[44:45], v[60:61], v[106:107], v[10:11] op_sel_hi:[1,0,1] neg_lo:[1,0,0] neg_hi:[1,0,0]
	v_lshlrev_b32_e32 v10, 16, v7
	v_and_b32_e32 v11, 0xffff0000, v7
	v_lshlrev_b32_e32 v12, 16, v6
	v_and_b32_e32 v13, 0xffff0000, v6
	v_pk_mul_f32 v[138:139], v[118:119], v[118:119]
	v_pk_fma_f32 v[10:11], v[34:35], v[106:107], v[10:11] op_sel_hi:[1,0,1] neg_lo:[1,0,0] neg_hi:[1,0,0]
	v_pk_fma_f32 v[12:13], v[32:33], v[106:107], v[12:13] op_sel_hi:[1,0,1] neg_lo:[1,0,0] neg_hi:[1,0,0]
	v_add_f32_e32 v33, v132, v133
	v_add_f32_e32 v106, v134, v135
	v_pk_mul_f32 v[136:137], v[86:87], v[86:87]
	v_add_f32_e32 v33, v106, v33
	v_add_f32_e32 v106, v138, v139
	v_pk_mul_f32 v[142:143], v[120:121], v[120:121]
	v_add_f32_e32 v32, v136, v137
	v_add_f32_e32 v33, v106, v33
	v_pk_mul_f32 v[140:141], v[90:91], v[90:91]
	v_add_f32_e32 v32, v32, v33
	v_add_f32_e32 v33, v142, v143
	v_pk_mul_f32 v[122:123], v[92:93], v[92:93]
	v_add_f32_e32 v32, v33, v32
	v_add_f32_e32 v33, v140, v141
	v_pk_mul_f32 v[146:147], v[88:89], v[88:89]
	v_add_f32_e32 v32, v33, v32
	v_add_f32_e32 v33, v122, v123
	v_pk_mul_f32 v[124:125], v[94:95], v[94:95]
	v_add_f32_e32 v32, v33, v32
	v_add_f32_e32 v33, v146, v147
	v_pk_mul_f32 v[148:149], v[84:85], v[84:85]
	v_add_f32_e32 v32, v33, v32
	v_add_f32_e32 v33, v124, v125
	v_pk_mul_f32 v[126:127], v[82:83], v[82:83]
	v_add_f32_e32 v32, v33, v32
	v_add_f32_e32 v33, v148, v149
	v_pk_mul_f32 v[150:151], v[80:81], v[80:81]
	v_add_f32_e32 v32, v33, v32
	v_add_f32_e32 v33, v126, v127
	v_pk_mul_f32 v[128:129], v[72:73], v[72:73]
	v_add_f32_e32 v32, v33, v32
	v_add_f32_e32 v33, v150, v151
	v_pk_mul_f32 v[152:153], v[74:75], v[74:75]
	v_add_f32_e32 v32, v33, v32
	v_add_f32_e32 v33, v128, v129
	v_pk_mul_f32 v[76:77], v[70:71], v[70:71]
	v_add_f32_e32 v32, v33, v32
	v_add_f32_e32 v33, v152, v153
	v_pk_mul_f32 v[78:79], v[68:69], v[68:69]
	v_add_f32_e32 v32, v33, v32
	v_add_f32_e32 v33, v76, v77
	v_pk_mul_f32 v[96:97], v[66:67], v[66:67]
	v_add_f32_e32 v32, v33, v32
	v_add_f32_e32 v33, v78, v79
	v_pk_mul_f32 v[130:131], v[64:65], v[64:65]
	v_add_f32_e32 v32, v33, v32
	v_add_f32_e32 v33, v96, v97
	v_pk_mul_f32 v[98:99], v[52:53], v[52:53]
	v_add_f32_e32 v32, v33, v32
	v_add_f32_e32 v33, v130, v131
	v_pk_mul_f32 v[54:55], v[50:51], v[50:51]
	v_add_f32_e32 v32, v33, v32
	v_add_f32_e32 v33, v98, v99
	v_pk_mul_f32 v[56:57], v[48:49], v[48:49]
	v_add_f32_e32 v32, v33, v32
	v_add_f32_e32 v33, v54, v55
	v_pk_mul_f32 v[58:59], v[46:47], v[46:47]
	v_add_f32_e32 v32, v33, v32
	v_add_f32_e32 v33, v56, v57
	v_pk_mul_f32 v[60:61], v[44:45], v[44:45]
	v_add_f32_e32 v32, v33, v32
	v_add_f32_e32 v33, v58, v59
	v_pk_mul_f32 v[62:63], v[42:43], v[42:43]
	v_add_f32_e32 v32, v33, v32
	v_add_f32_e32 v33, v60, v61
	v_pk_mul_f32 v[6:7], v[12:13], v[12:13]
	v_add_f32_e32 v32, v33, v32
	v_add_f32_e32 v33, v62, v63
	v_pk_mul_f32 v[34:35], v[10:11], v[10:11]
	v_add_f32_e32 v32, v33, v32
	v_add_f32_e32 v6, v6, v7
	v_add_f32_e32 v6, v6, v32
	v_add_f32_e32 v7, v34, v35
	v_add_f32_e32 v6, v7, v6
	v_add_f32_e32 v6, v104, v6
	v_add_f32_e32 v6, v105, v6
	v_add_f32_e32 v6, v108, v6
	v_add_f32_e32 v6, v109, v6
	v_add_f32_e32 v6, v114, v6
	v_add_f32_e32 v6, v115, v6
	ds_bpermute_b32 v7, v166, v6
	s_waitcnt vmcnt(27)
	s_nop 1
	v_mov_b64_e32 v[2:3], v[204:205]
	v_mov_b64_e32 v[4:5], v[206:207]
	s_waitcnt vmcnt(26)
; DI unsigned pk2(float a, float b) { f32x2 v = {a, b}; return __builtin_bit_cast(unsigned, __builtin_convertvector(v, bf2_t)); }
; DI float bf_lo(unsigned u) { return __uint_as_float(u << 16); }
; DI float bf_hi(unsigned u) { return __uint_as_float(u & 0xffff0000u); }
; DI void diff_item(const Params& P, int layer, int b, int hd, int qt, float lam, float omli, float negM2, char* lds) {
;     ...
;     const float rs = __builtin_amdgcn_rsqf(ss * (1.f / 128.f) + kEps) * omli;
;     const float* sw = P.subln + layer * 128;
; #pragma unroll
;     for (int db = 0; db < 4; ++db) {
; #pragma unroll
;         for (int q4 = 0; q4 < 4; ++q4) {
;             const int dv = 32 * db + 8 * q4 + 4 * h;
;             const f32x4 w4 = *(const f32x4*)(sw + dv);
;             const u32x2 z2 = *(const u32x2*)(dz + tokq * 512 + hd * 128 + dv);
;             const float r0 = O[db][4 * q4] * rs * w4[0] * bf_lo(z2[0]), r1 = O[db][4 * q4 + 1] * rs * w4[1] * bf_hi(z2[0]);
;             const float r2 = O[db][4 * q4 + 2] * rs * w4[2] * bf_lo(z2[1]), r3 = O[db][4 * q4 + 3] * rs * w4[3] * bf_hi(z2[1]);
;             u32x2 o = {pk2(r0, r1), pk2(r2, r3)};
;             *(u32x2*)(dq + tokq * 512 + hd * 128 + dv) = o;
;         }
	s_nop 1
	v_mov_b64_e32 v[110:111], v[154:155]
	v_lshlrev_b32_e32 v56, 16, v110
	v_and_b32_e32 v57, 0xffff0000, v110
	v_lshlrev_b32_e32 v58, 16, v111
	v_and_b32_e32 v59, 0xffff0000, v111
	s_waitcnt lgkmcnt(0)
	v_add_f32_e32 v6, v6, v7
	v_fmamk_f32 v6, v6, 0x3c000000, v163
	v_rsq_f32_e32 v60, v6
	v_lshl_add_u64 v[6:7], v[144:145], 0, v[0:1]
	v_mul_f32_e32 v0, v168, v60
	v_pk_mul_f32 v[60:61], v[116:117], v[0:1] op_sel_hi:[1,0]
	s_nop 0
	v_pk_mul_f32 v[2:3], v[2:3], v[60:61]
	s_nop 0
	v_pk_mul_f32 v[2:3], v[2:3], v[56:57]
	v_pk_mul_f32 v[56:57], v[112:113], v[0:1] op_sel_hi:[1,0]
	v_cvt_pk_bf16_f32 v2, v2, v3
	v_pk_mul_f32 v[4:5], v[4:5], v[56:57]
	s_waitcnt vmcnt(24)
	s_nop 1
	v_mov_b64_e32 v[32:33], v[156:157]
	v_lshlrev_b32_e32 v56, 16, v32
	v_pk_mul_f32 v[4:5], v[4:5], v[58:59]
	v_pk_mul_f32 v[58:59], v[118:119], v[0:1] op_sel_hi:[1,0]
	v_cvt_pk_bf16_f32 v3, v4, v5
	global_store_dwordx2 v[6:7], v[2:3], off
	v_and_b32_e32 v57, 0xffff0000, v32
	v_lshlrev_b32_e32 v32, 16, v33
	v_and_b32_e32 v33, 0xffff0000, v33
	s_waitcnt vmcnt(23)
	s_nop 1
	v_mov_b64_e32 v[34:35], v[158:159]
	s_waitcnt vmcnt(21)
	s_nop 1
	v_mov_b64_e32 v[54:55], v[160:161]
	s_waitcnt vmcnt(26)
	s_nop 1
	v_mov_b64_e32 v[2:3], v[208:209]
	v_mov_b64_e32 v[4:5], v[210:211]
	v_pk_mul_f32 v[2:3], v[2:3], v[58:59]
	s_nop 0
	v_pk_mul_f32 v[2:3], v[2:3], v[56:57]
	v_pk_mul_f32 v[56:57], v[86:87], v[0:1] op_sel_hi:[1,0]
	v_cvt_pk_bf16_f32 v2, v2, v3
	v_pk_mul_f32 v[4:5], v[4:5], v[56:57]
	v_pk_mul_f32 v[56:57], v[90:91], v[0:1] op_sel_hi:[1,0]
	v_pk_mul_f32 v[4:5], v[4:5], v[32:33]
	v_pk_mul_f32 v[32:33], v[120:121], v[0:1] op_sel_hi:[1,0]
	v_cvt_pk_bf16_f32 v3, v4, v5
	global_store_dwordx2 v[6:7], v[2:3], off offset:16
	v_lshlrev_b32_e32 v58, 16, v34
	v_and_b32_e32 v59, 0xffff0000, v34
	v_lshlrev_b32_e32 v34, 16, v35
	v_and_b32_e32 v35, 0xffff0000, v35
	s_waitcnt vmcnt(25)
	s_nop 1
	v_mov_b64_e32 v[2:3], v[212:213]
	v_mov_b64_e32 v[4:5], v[214:215]
	v_pk_mul_f32 v[2:3], v[2:3], v[32:33]
	v_pk_mul_f32 v[4:5], v[4:5], v[56:57]
	v_pk_mul_f32 v[2:3], v[2:3], v[58:59]
	v_pk_mul_f32 v[4:5], v[4:5], v[34:35]
	v_cvt_pk_bf16_f32 v2, v2, v3
	v_cvt_pk_bf16_f32 v3, v4, v5
	global_store_dwordx2 v[6:7], v[2:3], off offset:32
	v_pk_mul_f32 v[32:33], v[92:93], v[0:1] op_sel_hi:[1,0]
	v_pk_mul_f32 v[34:35], v[88:89], v[0:1] op_sel_hi:[1,0]
	v_lshlrev_b32_e32 v56, 16, v54
	v_and_b32_e32 v57, 0xffff0000, v54
	v_lshlrev_b32_e32 v54, 16, v55
	v_and_b32_e32 v55, 0xffff0000, v55
	s_waitcnt vmcnt(24)
	s_nop 1
	v_mov_b64_e32 v[2:3], v[216:217]
	v_mov_b64_e32 v[4:5], v[218:219]
	global_load_dwordx4 v[204:207], v107, s[6:7] offset:384
	global_load_dwordx4 v[208:211], v107, s[6:7] offset:416
	global_load_dwordx4 v[212:215], v107, s[6:7] offset:448
	global_load_dwordx4 v[216:219], v107, s[6:7] offset:480
	v_pk_mul_f32 v[2:3], v[2:3], v[32:33]
	v_pk_mul_f32 v[4:5], v[4:5], v[34:35]
	v_pk_mul_f32 v[2:3], v[2:3], v[56:57]
	v_pk_mul_f32 v[4:5], v[4:5], v[54:55]
	v_cvt_pk_bf16_f32 v2, v2, v3
	v_cvt_pk_bf16_f32 v3, v4, v5
	global_store_dwordx2 v[6:7], v[2:3], off offset:48
	s_nop 0
	v_pk_mul_f32 v[34:35], v[94:95], v[0:1] op_sel_hi:[1,0]
	s_waitcnt vmcnt(27)
	s_nop 1
	v_mov_b64_e32 v[2:3], v[220:221]
	v_mov_b64_e32 v[4:5], v[222:223]
	v_pk_mul_f32 v[2:3], v[2:3], v[34:35]
	s_waitcnt vmcnt(26)
	s_nop 1
	v_mov_b64_e32 v[32:33], v[164:165]
	v_lshlrev_b32_e32 v34, 16, v32
	v_and_b32_e32 v35, 0xffff0000, v32
	v_pk_mul_f32 v[2:3], v[2:3], v[34:35]
	v_pk_mul_f32 v[34:35], v[84:85], v[0:1] op_sel_hi:[1,0]
	v_lshlrev_b32_e32 v32, 16, v33
	v_pk_mul_f32 v[4:5], v[4:5], v[34:35]
	v_and_b32_e32 v33, 0xffff0000, v33
	v_pk_mul_f32 v[4:5], v[4:5], v[32:33]
	v_cvt_pk_bf16_f32 v2, v2, v3
	v_cvt_pk_bf16_f32 v3, v4, v5
	global_store_dwordx2 v[6:7], v[2:3], off offset:64
	s_nop 0
	v_pk_mul_f32 v[34:35], v[82:83], v[0:1] op_sel_hi:[1,0]
	s_waitcnt vmcnt(26)
	s_nop 1
	v_mov_b64_e32 v[2:3], v[224:225]
	v_mov_b64_e32 v[4:5], v[226:227]
	v_pk_mul_f32 v[2:3], v[2:3], v[34:35]
	s_waitcnt vmcnt(25)
	s_nop 1
	v_mov_b64_e32 v[32:33], v[170:171]
	v_lshlrev_b32_e32 v34, 16, v32
	v_and_b32_e32 v35, 0xffff0000, v32
	v_pk_mul_f32 v[2:3], v[2:3], v[34:35]
	v_pk_mul_f32 v[34:35], v[80:81], v[0:1] op_sel_hi:[1,0]
	v_lshlrev_b32_e32 v32, 16, v33
	v_pk_mul_f32 v[4:5], v[4:5], v[34:35]
	v_and_b32_e32 v33, 0xffff0000, v33
	v_pk_mul_f32 v[4:5], v[4:5], v[32:33]
	v_cvt_pk_bf16_f32 v2, v2, v3
	v_cvt_pk_bf16_f32 v3, v4, v5
	global_store_dwordx2 v[6:7], v[2:3], off offset:80
	s_nop 0
	v_pk_mul_f32 v[34:35], v[72:73], v[0:1] op_sel_hi:[1,0]
	s_waitcnt vmcnt(25)
	s_nop 1
	v_mov_b64_e32 v[2:3], v[228:229]
	v_mov_b64_e32 v[4:5], v[230:231]
	v_pk_mul_f32 v[2:3], v[2:3], v[34:35]
	s_waitcnt vmcnt(24)
	s_nop 1
	v_mov_b64_e32 v[32:33], v[172:173]
	v_lshlrev_b32_e32 v34, 16, v32
	v_and_b32_e32 v35, 0xffff0000, v32
	v_pk_mul_f32 v[2:3], v[2:3], v[34:35]
	v_pk_mul_f32 v[34:35], v[74:75], v[0:1] op_sel_hi:[1,0]
	v_lshlrev_b32_e32 v32, 16, v33
	v_pk_mul_f32 v[4:5], v[4:5], v[34:35]
	v_and_b32_e32 v33, 0xffff0000, v33
	v_pk_mul_f32 v[4:5], v[4:5], v[32:33]
	v_cvt_pk_bf16_f32 v2, v2, v3
	v_cvt_pk_bf16_f32 v3, v4, v5
	global_store_dwordx2 v[6:7], v[2:3], off offset:96
	s_nop 0
	v_pk_mul_f32 v[34:35], v[70:71], v[0:1] op_sel_hi:[1,0]
	s_waitcnt vmcnt(24)
	s_nop 1
	v_mov_b64_e32 v[2:3], v[232:233]
	v_mov_b64_e32 v[4:5], v[234:235]
	v_pk_mul_f32 v[2:3], v[2:3], v[34:35]
	s_waitcnt vmcnt(23)
	s_nop 1
	v_mov_b64_e32 v[32:33], v[184:185]
	v_lshlrev_b32_e32 v34, 16, v32
	v_and_b32_e32 v35, 0xffff0000, v32
	v_pk_mul_f32 v[2:3], v[2:3], v[34:35]
	v_pk_mul_f32 v[34:35], v[68:69], v[0:1] op_sel_hi:[1,0]
	v_lshlrev_b32_e32 v32, 16, v33
	v_pk_mul_f32 v[4:5], v[4:5], v[34:35]
	v_and_b32_e32 v33, 0xffff0000, v33
	v_pk_mul_f32 v[4:5], v[4:5], v[32:33]
	v_cvt_pk_bf16_f32 v2, v2, v3
	v_cvt_pk_bf16_f32 v3, v4, v5
	global_store_dwordx2 v[6:7], v[2:3], off offset:112
	s_nop 0
	v_pk_mul_f32 v[34:35], v[66:67], v[0:1] op_sel_hi:[1,0]
	s_waitcnt vmcnt(23)
; DI unsigned pk2(float a, float b) { f32x2 v = {a, b}; return __builtin_bit_cast(unsigned, __builtin_convertvector(v, bf2_t)); }
; DI float bf_lo(unsigned u) { return __uint_as_float(u << 16); }
; DI float bf_hi(unsigned u) { return __uint_as_float(u & 0xffff0000u); }
; DI void diff_item(const Params& P, int layer, int b, int hd, int qt, float lam, float omli, float negM2, char* lds) {
;     ...
; #pragma unroll
;     for (int db = 0; db < 4; ++db) {
; #pragma unroll
;         for (int q4 = 0; q4 < 4; ++q4) {
;             const int dv = 32 * db + 8 * q4 + 4 * h;
;             const f32x4 w4 = *(const f32x4*)(sw + dv);
;             const u32x2 z2 = *(const u32x2*)(dz + tokq * 512 + hd * 128 + dv);
;             const float r0 = O[db][4 * q4] * rs * w4[0] * bf_lo(z2[0]), r1 = O[db][4 * q4 + 1] * rs * w4[1] * bf_hi(z2[0]);
;             const float r2 = O[db][4 * q4 + 2] * rs * w4[2] * bf_lo(z2[1]), r3 = O[db][4 * q4 + 3] * rs * w4[3] * bf_hi(z2[1]);
;             u32x2 o = {pk2(r0, r1), pk2(r2, r3)};
;             *(u32x2*)(dq + tokq * 512 + hd * 128 + dv) = o;
;         }
;         __builtin_amdgcn_sched_barrier(0);
;     }
	s_nop 1
	v_mov_b64_e32 v[2:3], v[236:237]
	v_mov_b64_e32 v[4:5], v[238:239]
	v_pk_mul_f32 v[2:3], v[2:3], v[34:35]
	s_waitcnt vmcnt(22)
	s_nop 1
	v_mov_b64_e32 v[32:33], v[186:187]
	v_lshlrev_b32_e32 v34, 16, v32
	v_and_b32_e32 v35, 0xffff0000, v32
	v_pk_mul_f32 v[2:3], v[2:3], v[34:35]
	v_pk_mul_f32 v[34:35], v[64:65], v[0:1] op_sel_hi:[1,0]
	v_lshlrev_b32_e32 v32, 16, v33
	v_pk_mul_f32 v[4:5], v[4:5], v[34:35]
	v_and_b32_e32 v33, 0xffff0000, v33
	v_pk_mul_f32 v[4:5], v[4:5], v[32:33]
	v_cvt_pk_bf16_f32 v2, v2, v3
	v_cvt_pk_bf16_f32 v3, v4, v5
	global_store_dwordx2 v[6:7], v[2:3], off offset:128
	s_nop 0
	v_pk_mul_f32 v[34:35], v[52:53], v[0:1] op_sel_hi:[1,0]
	s_waitcnt vmcnt(22)
	s_nop 1
	v_mov_b64_e32 v[2:3], v[240:241]
	v_mov_b64_e32 v[4:5], v[242:243]
	v_pk_mul_f32 v[2:3], v[2:3], v[34:35]
	s_waitcnt vmcnt(21)
	s_nop 1
	v_mov_b64_e32 v[32:33], v[188:189]
	v_lshlrev_b32_e32 v34, 16, v32
	v_and_b32_e32 v35, 0xffff0000, v32
	v_pk_mul_f32 v[2:3], v[2:3], v[34:35]
	v_pk_mul_f32 v[34:35], v[50:51], v[0:1] op_sel_hi:[1,0]
	v_lshlrev_b32_e32 v32, 16, v33
	v_pk_mul_f32 v[4:5], v[4:5], v[34:35]
	v_and_b32_e32 v33, 0xffff0000, v33
	v_pk_mul_f32 v[4:5], v[4:5], v[32:33]
	v_cvt_pk_bf16_f32 v2, v2, v3
	v_cvt_pk_bf16_f32 v3, v4, v5
	global_store_dwordx2 v[6:7], v[2:3], off offset:144
	s_nop 0
	v_pk_mul_f32 v[34:35], v[48:49], v[0:1] op_sel_hi:[1,0]
	s_waitcnt vmcnt(21)
	s_nop 1
	v_mov_b64_e32 v[2:3], v[244:245]
	v_mov_b64_e32 v[4:5], v[246:247]
	v_pk_mul_f32 v[2:3], v[34:35], v[2:3]
	s_waitcnt vmcnt(20)
	s_nop 1
	v_mov_b64_e32 v[32:33], v[190:191]
	v_lshlrev_b32_e32 v34, 16, v32
	v_and_b32_e32 v35, 0xffff0000, v32
	v_pk_mul_f32 v[2:3], v[2:3], v[34:35]
	v_pk_mul_f32 v[34:35], v[46:47], v[0:1] op_sel_hi:[1,0]
	v_lshlrev_b32_e32 v32, 16, v33
	v_pk_mul_f32 v[4:5], v[34:35], v[4:5]
	v_and_b32_e32 v33, 0xffff0000, v33
	v_pk_mul_f32 v[4:5], v[4:5], v[32:33]
	v_cvt_pk_bf16_f32 v2, v2, v3
	v_cvt_pk_bf16_f32 v3, v4, v5
	global_store_dwordx2 v[6:7], v[2:3], off offset:160
	s_nop 0
	v_pk_mul_f32 v[34:35], v[44:45], v[0:1] op_sel_hi:[1,0]
	s_waitcnt vmcnt(20)
	s_nop 1
	v_mov_b64_e32 v[2:3], v[248:249]
	v_mov_b64_e32 v[4:5], v[250:251]
	v_pk_mul_f32 v[2:3], v[34:35], v[2:3]
	s_waitcnt vmcnt(19)
	s_nop 1
	v_mov_b64_e32 v[32:33], v[192:193]
	v_lshlrev_b32_e32 v34, 16, v32
	v_and_b32_e32 v35, 0xffff0000, v32
	v_pk_mul_f32 v[2:3], v[2:3], v[34:35]
	v_pk_mul_f32 v[34:35], v[42:43], v[0:1] op_sel_hi:[1,0]
	v_lshlrev_b32_e32 v32, 16, v33
	v_pk_mul_f32 v[4:5], v[34:35], v[4:5]
	v_and_b32_e32 v33, 0xffff0000, v33
	v_pk_mul_f32 v[4:5], v[4:5], v[32:33]
	v_cvt_pk_bf16_f32 v2, v2, v3
	v_cvt_pk_bf16_f32 v3, v4, v5
	global_store_dwordx2 v[6:7], v[2:3], off offset:176
	s_nop 0
	v_pk_mul_f32 v[12:13], v[12:13], v[0:1] op_sel_hi:[1,0]
	v_pk_mul_f32 v[10:11], v[10:11], v[0:1] op_sel_hi:[1,0]
	s_waitcnt vmcnt(12)
	s_nop 1
	v_mov_b64_e32 v[2:3], v[204:205]
	v_mov_b64_e32 v[4:5], v[206:207]
	v_pk_mul_f32 v[2:3], v[12:13], v[2:3]
	s_waitcnt vmcnt(19)
	s_nop 1
	v_mov_b64_e32 v[32:33], v[194:195]
	v_lshlrev_b32_e32 v12, 16, v32
	v_and_b32_e32 v13, 0xffff0000, v32
	v_pk_mul_f32 v[4:5], v[10:11], v[4:5]
	v_lshlrev_b32_e32 v10, 16, v33
	v_and_b32_e32 v11, 0xffff0000, v33
	v_pk_mul_f32 v[2:3], v[2:3], v[12:13]
	v_pk_mul_f32 v[4:5], v[4:5], v[10:11]
	v_cvt_pk_bf16_f32 v2, v2, v3
	v_cvt_pk_bf16_f32 v3, v4, v5
	global_store_dwordx2 v[6:7], v[2:3], off offset:192
	s_nop 0
	v_mov_b32_e32 v12, v100
	v_mov_b32_e32 v13, v102
	v_pk_mul_f32 v[12:13], v[12:13], v[0:1] op_sel_hi:[1,0]
	v_mov_b32_e32 v102, v101
	s_waitcnt vmcnt(12)
	s_nop 1
	v_mov_b64_e32 v[2:3], v[208:209]
	v_mov_b64_e32 v[4:5], v[210:211]
	v_pk_mul_f32 v[2:3], v[12:13], v[2:3]
	s_waitcnt vmcnt(19)
	s_nop 1
	v_mov_b64_e32 v[10:11], v[196:197]
	v_lshlrev_b32_e32 v12, 16, v10
	v_and_b32_e32 v13, 0xffff0000, v10
	v_pk_mul_f32 v[2:3], v[2:3], v[12:13]
	v_pk_mul_f32 v[12:13], v[102:103], v[0:1] op_sel_hi:[1,0]
	v_lshlrev_b32_e32 v10, 16, v11
	v_pk_mul_f32 v[4:5], v[12:13], v[4:5]
	v_and_b32_e32 v11, 0xffff0000, v11
	v_pk_mul_f32 v[4:5], v[4:5], v[10:11]
	v_cvt_pk_bf16_f32 v2, v2, v3
	v_cvt_pk_bf16_f32 v3, v4, v5
	global_store_dwordx2 v[6:7], v[2:3], off offset:208
	s_nop 0
	v_mov_b32_e32 v12, v38
	v_mov_b32_e32 v13, v40
	v_pk_mul_f32 v[12:13], v[12:13], v[0:1] op_sel_hi:[1,0]
	v_mov_b32_e32 v40, v39
	s_waitcnt vmcnt(12)
	s_nop 1
	v_mov_b64_e32 v[2:3], v[212:213]
	v_mov_b64_e32 v[4:5], v[214:215]
	v_pk_mul_f32 v[2:3], v[12:13], v[2:3]
	s_waitcnt vmcnt(19)
	s_nop 1
	v_mov_b64_e32 v[10:11], v[198:199]
	v_lshlrev_b32_e32 v12, 16, v10
	v_and_b32_e32 v13, 0xffff0000, v10
	v_pk_mul_f32 v[2:3], v[2:3], v[12:13]
	v_pk_mul_f32 v[12:13], v[40:41], v[0:1] op_sel_hi:[1,0]
	v_lshlrev_b32_e32 v10, 16, v11
	v_pk_mul_f32 v[4:5], v[12:13], v[4:5]
	v_and_b32_e32 v11, 0xffff0000, v11
	v_pk_mul_f32 v[4:5], v[4:5], v[10:11]
	v_cvt_pk_bf16_f32 v2, v2, v3
	v_cvt_pk_bf16_f32 v3, v4, v5
	global_store_dwordx2 v[6:7], v[2:3], off offset:224
	s_nop 0
	v_mov_b32_e32 v12, v8
	v_mov_b32_e32 v13, v14
	v_mov_b32_e32 v14, v9
	v_pk_mul_f32 v[12:13], v[12:13], v[0:1] op_sel_hi:[1,0]
	v_pk_mul_f32 v[8:9], v[14:15], v[0:1] op_sel_hi:[1,0]
	s_waitcnt vmcnt(12)
	s_nop 1
	v_mov_b64_e32 v[2:3], v[216:217]
	v_mov_b64_e32 v[4:5], v[218:219]
	v_pk_mul_f32 v[2:3], v[12:13], v[2:3]
	s_waitcnt vmcnt(19)
	s_nop 1
	v_mov_b64_e32 v[10:11], v[200:201]
	v_lshlrev_b32_e32 v12, 16, v10
	v_and_b32_e32 v13, 0xffff0000, v10
	v_pk_mul_f32 v[4:5], v[8:9], v[4:5]
	v_lshlrev_b32_e32 v8, 16, v11
	v_and_b32_e32 v9, 0xffff0000, v11
	v_pk_mul_f32 v[2:3], v[2:3], v[12:13]
	v_pk_mul_f32 v[4:5], v[4:5], v[8:9]
	v_cvt_pk_bf16_f32 v2, v2, v3
	v_cvt_pk_bf16_f32 v3, v4, v5
	global_store_dwordx2 v[6:7], v[2:3], off offset:240
	s_and_b64 vcc, exec, s[24:25]
	s_cbranch_vccnz .LBB0_80
